# cache policy for read-once streams: nt hint on the prologue's f32 weight loads (each line is read once)
# baseline (speedup 1.0000x reference)
; __device__ __forceinline__ unsigned cvt_pk_bf16(float lo, float hi) { unsigned r; asm volatile("v_cvt_pk_bf16_f32 %0, %1, %2" : "=v"(r) : "v"(lo), "v"(hi)); return r; }
; __device__ __forceinline__ void prologue_wgu(const Args& a, unsigned char* ws, LAS unsigned char* lds, int blk, int G, int tid_) {
;     ...
;         for (int bt = 0; bt < 4; ++bt) {
;             const int kb = 256 * wave + 64 * bt + 2 * p;
;             float v0[16], v1[16]; f32x2 gg[16];
; #pragma unroll
;             for (int j = 0; j < 16; ++j) { const float* wp = W + (size_t)(kb + 4 * j) * DFF; v0[j] = wp[0]; v1[j] = wp[DFF]; gg[j] = *(const f32x2*)(gain + kb + 4 * j); }
; #pragma unroll
;             for (int j = 0; j < 16; ++j) { const int k = kb + 4 * j; const float p0 = v0[j] * gg[j].x, p1 = v1[j] * gg[j].y;
;                 const unsigned w = cvt_pk_bf16(p0, p1);
;                 mx = fmaxf(mx, fmaxf(fabsf(p0), fabsf(p1)));
;                 const int kp = k >> 1;
;                 T[kp * 32 + (c ^ (((kp >> 3) & 7) << 2))] = w; }
.LBB0_19:
	v_add_u32_e32 v14, s31, v18
	v_mad_i64_i32 v[32:33], s[8:9], v14, s43, v[12:13]
	v_add_u32_e32 v31, 4, v14
	global_load_dword v98, v[32:33], off nt
	v_add_co_u32_e32 v32, vcc, 0x5000, v32
	v_add_u32_e32 v64, 16, v14
	v_add_u32_e32 v65, 20, v14
	v_mad_i64_i32 v[34:35], s[8:9], v31, s43, v[12:13]
	v_addc_co_u32_e32 v33, vcc, 0, v33, vcc
	v_add_u32_e32 v36, 8, v14
	v_add_u32_e32 v66, 24, v14
	v_mad_i64_i32 v[40:41], s[8:9], v64, s43, v[12:13]
	v_mad_i64_i32 v[42:43], s[8:9], v65, s43, v[12:13]
	v_lshrrev_b32_e32 v96, 2, v64
	v_lshrrev_b32_e32 v65, 2, v65
	v_add_co_u32_e32 v64, vcc, 0x5000, v34
	v_mad_i64_i32 v[36:37], s[8:9], v36, s43, v[12:13]
	v_lshrrev_b32_e32 v97, 2, v66
	v_bitop3_b32 v112, v65, v4, 20 bitop3:0x6c
	v_addc_co_u32_e32 v65, vcc, 0, v35, vcc
	v_ashrrev_i32_e32 v15, 31, v14
	v_add_u32_e32 v38, 12, v14
	v_bitop3_b32 v111, v96, v4, 20 bitop3:0x6c
	v_bitop3_b32 v97, v97, v4, 20 bitop3:0x6c
	v_add_co_u32_e32 v96, vcc, 0x5000, v36
	v_add_u32_e32 v67, 28, v14
	v_add_u32_e32 v68, 32, v14
	v_add_u32_e32 v69, 36, v14
	v_add_u32_e32 v70, 40, v14
	v_add_u32_e32 v71, 44, v14
	v_add_u32_e32 v72, 48, v14
	v_add_u32_e32 v73, 52, v14
	v_add_u32_e32 v74, 56, v14
	v_add_u32_e32 v75, 60, v14
	v_lshrrev_b32_e32 v76, 2, v14
	v_lshl_add_u64 v[14:15], v[14:15], 2, s[36:37]
	v_mad_i64_i32 v[38:39], s[8:9], v38, s43, v[12:13]
	v_lshl_add_u32 v113, v97, 2, v6
	v_addc_co_u32_e32 v97, vcc, 0, v37, vcc
	v_mad_i64_i32 v[44:45], s[8:9], v66, s43, v[12:13]
	v_mad_i64_i32 v[46:47], s[8:9], v67, s43, v[12:13]
	v_mad_i64_i32 v[48:49], s[8:9], v68, s43, v[12:13]
	v_mad_i64_i32 v[50:51], s[8:9], v69, s43, v[12:13]
	v_mad_i64_i32 v[52:53], s[8:9], v70, s43, v[12:13]
	v_mad_i64_i32 v[54:55], s[8:9], v71, s43, v[12:13]
	v_mad_i64_i32 v[56:57], s[8:9], v72, s43, v[12:13]
	v_mad_i64_i32 v[58:59], s[8:9], v73, s43, v[12:13]
	v_mad_i64_i32 v[60:61], s[8:9], v74, s43, v[12:13]
	v_mad_i64_i32 v[62:63], s[8:9], v75, s43, v[12:13]
	v_bitop3_b32 v31, v76, v4, 16 bitop3:0x6c
	v_lshrrev_b32_e32 v99, 2, v67
	v_lshrrev_b32_e32 v100, 2, v68
	v_lshrrev_b32_e32 v101, 2, v69
	v_lshrrev_b32_e32 v102, 2, v70
	v_lshrrev_b32_e32 v103, 2, v71
	v_lshrrev_b32_e32 v104, 2, v72
	v_lshrrev_b32_e32 v105, 2, v73
	v_lshrrev_b32_e32 v106, 2, v74
	v_lshrrev_b32_e32 v107, 2, v75
	global_load_dword v108, v[40:41], off nt
	global_load_dword v109, v[48:49], off nt
	global_load_dword v110, v[56:57], off nt
	global_load_dwordx2 v[66:67], v[14:15], off nt
	global_load_dwordx2 v[68:69], v[14:15], off offset:16 nt
	global_load_dwordx2 v[70:71], v[14:15], off offset:32 nt
	global_load_dwordx2 v[72:73], v[14:15], off offset:48 nt
	global_load_dwordx2 v[74:75], v[14:15], off offset:64 nt
	global_load_dwordx2 v[76:77], v[14:15], off offset:80 nt
	global_load_dwordx2 v[78:79], v[14:15], off offset:96 nt
	global_load_dwordx2 v[80:81], v[14:15], off offset:112 nt
	global_load_dwordx2 v[82:83], v[14:15], off offset:128 nt
	global_load_dwordx2 v[84:85], v[14:15], off offset:144 nt
	global_load_dwordx2 v[86:87], v[14:15], off offset:160 nt
	global_load_dwordx2 v[88:89], v[14:15], off offset:176 nt
	global_load_dwordx2 v[90:91], v[14:15], off offset:192 nt
	global_load_dwordx2 v[92:93], v[14:15], off offset:208 nt
	global_load_dwordx2 v[94:95], v[14:15], off offset:224 nt
	s_nop 0
	global_load_dwordx2 v[14:15], v[14:15], off offset:240 nt
	s_nop 0
	global_load_dword v114, v[32:33], off offset:2048 nt
	global_load_dword v115, v[34:35], off nt
	s_nop 0
	global_load_dword v64, v[64:65], off offset:2048 nt
	s_nop 0
	global_load_dword v65, v[36:37], off nt
	v_add_co_u32_e32 v32, vcc, 0x5000, v38
	s_mov_b64 s[8:9], vcc
	v_add_co_u32_e32 v34, vcc, 0x5000, v40
	v_addc_co_u32_e64 v33, s[8:9], 0, v39, s[8:9]
	s_nop 0
	v_addc_co_u32_e32 v35, vcc, 0, v41, vcc
	global_load_dword v40, v[96:97], off offset:2048 nt
	s_nop 0
	global_load_dword v38, v[38:39], off nt
	v_lshl_add_u32 v31, v31, 2, v6
	global_load_dword v39, v[32:33], off offset:2048 nt
	v_add_co_u32_e32 v32, vcc, 0x5000, v42
	global_load_dword v41, v[34:35], off offset:2048 nt
	s_nop 0
	global_load_dword v42, v[42:43], off nt
	v_addc_co_u32_e32 v33, vcc, 0, v43, vcc
	v_add_co_u32_e32 v34, vcc, 0x5000, v44
	global_load_dword v43, v[32:33], off offset:2048 nt
	s_nop 0
	global_load_dword v44, v[44:45], off nt
	v_addc_co_u32_e32 v35, vcc, 0, v45, vcc
	v_add_co_u32_e32 v32, vcc, 0x5000, v46
	v_lshl_add_u32 v111, v111, 2, v6
	s_nop 0
	v_addc_co_u32_e32 v33, vcc, 0, v47, vcc
	v_add_co_u32_e32 v36, vcc, 0x5000, v48
	global_load_dword v45, v[34:35], off offset:2048 nt
	s_nop 0
	global_load_dword v46, v[46:47], off nt
	s_nop 0
	global_load_dword v47, v[32:33], off offset:2048 nt
	v_addc_co_u32_e32 v37, vcc, 0, v49, vcc
	v_add_co_u32_e32 v32, vcc, 0x5000, v50
	global_load_dword v48, v[36:37], off offset:2048 nt
	global_load_dword v49, v[50:51], off nt
	v_addc_co_u32_e32 v33, vcc, 0, v51, vcc
	v_add_co_u32_e32 v34, vcc, 0x5000, v52
	v_lshl_add_u32 v112, v112, 2, v6
	s_nop 0
	v_addc_co_u32_e32 v35, vcc, 0, v53, vcc
	v_add_co_u32_e32 v36, vcc, 0x5000, v54
	global_load_dword v50, v[32:33], off offset:2048 nt
	global_load_dword v51, v[52:53], off nt
	s_nop 0
	global_load_dword v52, v[34:35], off offset:2048 nt
	global_load_dword v53, v[54:55], off nt
	v_addc_co_u32_e32 v37, vcc, 0, v55, vcc
	v_add_co_u32_e32 v32, vcc, 0x5000, v56
	global_load_dword v36, v[36:37], off offset:2048 nt
	s_nop 0
	v_addc_co_u32_e32 v33, vcc, 0, v57, vcc
	v_add_co_u32_e32 v34, vcc, 0x5000, v58
	global_load_dword v37, v[32:33], off offset:2048 nt
	global_load_dword v54, v[58:59], off nt
	v_addc_co_u32_e32 v35, vcc, 0, v59, vcc
	v_add_co_u32_e32 v32, vcc, 0x5000, v60
	global_load_dword v55, v[34:35], off offset:2048 nt
	global_load_dword v56, v[60:61], off nt
	v_addc_co_u32_e32 v33, vcc, 0, v61, vcc
	v_add_co_u32_e32 v34, vcc, 0x5000, v62
	global_load_dword v32, v[32:33], off offset:2048 nt
	s_nop 0
	global_load_dword v33, v[62:63], off nt
	v_addc_co_u32_e32 v35, vcc, 0, v63, vcc
	global_load_dword v34, v[34:35], off offset:2048 nt
	s_waitcnt vmcnt(43)
; __device__ __forceinline__ unsigned cvt_pk_bf16(float lo, float hi) { unsigned r; asm volatile("v_cvt_pk_bf16_f32 %0, %1, %2" : "=v"(r) : "v"(lo), "v"(hi)); return r; }
; __device__ __forceinline__ void prologue_wgu(const Args& a, unsigned char* ws, LAS unsigned char* lds, int blk, int G, int tid_) {
;     ...
;             for (int j = 0; j < 16; ++j) { const int k = kb + 4 * j; const float p0 = v0[j] * gg[j].x, p1 = v1[j] * gg[j].y;
;                 const unsigned w = cvt_pk_bf16(p0, p1);
;                 mx = fmaxf(mx, fmaxf(fabsf(p0), fabsf(p1)));
;                 const int kp = k >> 1;
;                 T[kp * 32 + (c ^ (((kp >> 3) & 7) << 2))] = w; }
;         }
;         mx = fmaxf(mx, __shfl_xor(mx, 32));
;         if (p == 0) red[wave * 32 + c] = mx;
	v_mul_f32_e32 v35, v98, v66
	s_waitcnt vmcnt(39)
	v_mul_f32_e32 v57, v108, v74
	v_bitop3_b32 v99, v99, v4, 20 bitop3:0x6c
	v_bitop3_b32 v100, v100, v4, 24 bitop3:0x6c
	v_lshl_add_u32 v99, v99, 2, v6
	v_bitop3_b32 v101, v101, v4, 24 bitop3:0x6c
	v_lshl_add_u32 v100, v100, 2, v6
	s_waitcnt vmcnt(35)
	v_mul_f32_e32 v58, v109, v82
	s_waitcnt vmcnt(27)
	v_mul_f32_e32 v60, v114, v67
	s_waitcnt vmcnt(26)
	v_mul_f32_e32 v61, v115, v68
	s_waitcnt vmcnt(25)
	v_mul_f32_e32 v62, v64, v69
	v_max_f32_e64 v64, |v35|, |v60|
	v_cvt_pk_bf16_f32 v35, v35, v60
	ds_write_b32 v31, v35
	v_cvt_pk_bf16_f32 v35, v61, v62
	s_waitcnt vmcnt(24)
	v_mul_f32_e32 v63, v65, v70
	v_max_f32_e64 v60, |v61|, |v62|
	ds_write_b32 v31, v35 offset:256
	v_max3_f32 v30, v30, v64, v60
	v_bitop3_b32 v102, v102, v4, 24 bitop3:0x6c
	s_waitcnt vmcnt(23)
	v_mul_f32_e32 v40, v40, v71
	s_waitcnt vmcnt(22)
	v_mul_f32_e32 v38, v38, v72
	v_cvt_pk_bf16_f32 v35, v63, v40
	s_waitcnt vmcnt(21)
	v_mul_f32_e32 v39, v39, v73
	v_max_f32_e64 v60, |v63|, |v40|
	s_waitcnt vmcnt(20)
	v_mul_f32_e32 v40, v41, v75
	v_max_f32_e64 v41, |v38|, |v39|
	ds_write_b32 v31, v35 offset:512
	v_cvt_pk_bf16_f32 v35, v38, v39
	s_waitcnt vmcnt(19)
	v_mul_f32_e32 v38, v42, v76
	ds_write_b32 v31, v35 offset:768
	s_waitcnt vmcnt(18)
	v_mul_f32_e32 v31, v43, v77
	v_max3_f32 v30, v30, v60, v41
	v_cvt_pk_bf16_f32 v35, v57, v40
	v_max_f32_e64 v40, |v57|, |v40|
	ds_write_b32 v111, v35 offset:1024
	v_cvt_pk_bf16_f32 v41, v38, v31
	v_max_f32_e64 v31, |v38|, |v31|
	s_waitcnt vmcnt(17)
	v_mul_f32_e32 v39, v44, v78
	s_waitcnt vmcnt(16)
	v_mul_f32_e32 v35, v45, v79
	v_max3_f32 v30, v30, v40, v31
	ds_write_b32 v112, v41 offset:1280
	v_cvt_pk_bf16_f32 v31, v39, v35
	s_waitcnt vmcnt(15)
	v_mul_f32_e32 v38, v46, v80
	v_max_f32_e64 v35, |v39|, |v35|
	s_waitcnt vmcnt(14)
	v_mul_f32_e32 v39, v47, v81
	ds_write_b32 v113, v31 offset:1536
	v_cvt_pk_bf16_f32 v31, v38, v39
	v_max_f32_e64 v38, |v38|, |v39|
	s_waitcnt vmcnt(13)
	v_mul_f32_e32 v39, v48, v83
	ds_write_b32 v99, v31 offset:1792
	v_cvt_pk_bf16_f32 v31, v58, v39
	v_lshl_add_u32 v101, v101, 2, v6
	s_waitcnt vmcnt(12)
	v_mul_f32_e32 v40, v49, v84
	v_max3_f32 v30, v30, v35, v38
	s_waitcnt vmcnt(11)
	v_mul_f32_e32 v38, v50, v85
	ds_write_b32 v100, v31 offset:2048
	v_cvt_pk_bf16_f32 v31, v40, v38
	v_bitop3_b32 v103, v103, v4, 24 bitop3:0x6c
	v_lshl_add_u32 v102, v102, 2, v6
	v_max_f32_e64 v35, |v58|, |v39|
	s_waitcnt vmcnt(10)
	v_mul_f32_e32 v39, v51, v86
	v_max_f32_e64 v38, |v40|, |v38|
	s_waitcnt vmcnt(9)
	v_mul_f32_e32 v40, v52, v87
	ds_write_b32 v101, v31 offset:2304
	v_cvt_pk_bf16_f32 v31, v39, v40
	v_bitop3_b32 v104, v104, v4, 28 bitop3:0x6c
	v_lshl_add_u32 v103, v103, 2, v6
	s_waitcnt vmcnt(8)
	v_mul_f32_e32 v41, v53, v88
	s_waitcnt vmcnt(7)
	v_mul_f32_e32 v36, v36, v89
	ds_write_b32 v102, v31 offset:2560
	v_cvt_pk_bf16_f32 v31, v41, v36
	v_bitop3_b32 v105, v105, v4, 28 bitop3:0x6c
	v_lshl_add_u32 v104, v104, 2, v6
	v_mul_f32_e32 v59, v110, v90
	v_max3_f32 v30, v30, v35, v38
	v_max_f32_e64 v35, |v39|, |v40|
	v_max_f32_e64 v36, |v41|, |v36|
	s_waitcnt vmcnt(6)
	v_mul_f32_e32 v37, v37, v91
	ds_write_b32 v103, v31 offset:2816
	v_cvt_pk_bf16_f32 v31, v59, v37
	v_bitop3_b32 v106, v106, v4, 28 bitop3:0x6c
	v_lshl_add_u32 v105, v105, 2, v6
	s_waitcnt vmcnt(5)
	v_mul_f32_e32 v38, v54, v92
	v_max3_f32 v30, v30, v35, v36
	s_waitcnt vmcnt(4)
	v_mul_f32_e32 v36, v55, v93
	ds_write_b32 v104, v31 offset:3072
	v_cvt_pk_bf16_f32 v31, v38, v36
	v_lshl_add_u32 v106, v106, 2, v6
	v_max_f32_e64 v35, |v59|, |v37|
	s_waitcnt vmcnt(3)
	v_mul_f32_e32 v37, v56, v94
	v_max_f32_e64 v36, |v38|, |v36|
	s_waitcnt vmcnt(2)
	v_mul_f32_e32 v32, v32, v95
	s_waitcnt vmcnt(1)
	v_mul_f32_e32 v14, v33, v14
	ds_write_b32 v105, v31 offset:3328
	v_cvt_pk_bf16_f32 v31, v37, v32
	s_waitcnt vmcnt(0)
	v_mul_f32_e32 v15, v34, v15
	s_add_i32 s31, s31, 64
	v_bitop3_b32 v107, v107, v4, 28 bitop3:0x6c
	v_max3_f32 v30, v30, v35, v36
	v_max_f32_e64 v32, |v37|, |v32|
	ds_write_b32 v106, v31 offset:3584
	v_cvt_pk_bf16_f32 v31, v14, v15
	v_max_f32_e64 v14, |v14|, |v15|
	s_cmpk_eq_i32 s31, 0x100
	v_lshl_add_u32 v107, v107, 2, v6
	v_add_u32_e32 v6, 0x1000, v6
	v_max3_f32 v30, v30, v32, v14
	ds_write_b32 v107, v31 offset:3840
	s_cbranch_scc0 .LBB0_19
	v_and_b32_e32 v12, 64, v29
	v_xor_b32_e32 v6, 32, v29
	v_add_u32_e32 v12, 64, v12
	v_cmp_lt_i32_e32 vcc, v6, v12
	s_nop 1
	v_cndmask_b32_e32 v6, v29, v6, vcc
	v_lshlrev_b32_e32 v6, 2, v6
	ds_bpermute_b32 v6, v6, v30
	s_and_saveexec_b64 s[8:9], s[6:7]
	s_cbranch_execz .LBB0_22
	s_waitcnt lgkmcnt(0)
	v_max_f32_e32 v6, v6, v6
	v_max_f32_e32 v12, v30, v30
	v_max_f32_e32 v6, v12, v6
	ds_write_b32 v20, v6

; __device__ __forceinline__ void tr_item(const float* W, int ldw, int src_col0, int k0, const float* gain, bf16_t* WT, int K, int dst_row0, LAS float* scr, int lane) {
;     ...
;     const float* wp = W + (size_t)(k0 + (lane >> 5)) * ldw + src_col0 + (lane & 31);
; #pragma unroll
;     for (int i = 0; i < 32; ++i) v[i] = wp[(size_t)(2 * i) * ldw];
; __device__ __forceinline__ void prologue(const Args& a, unsigned char* ws, LAS unsigned char* lds, int gw, int ngw, int wave, int lane) {
;     ...
;         } else {
;             r -= 2 * IT_D + IT_WIN;
;             const float* W = a.in[13] + (size_t)l * DM * DM; const float* gain = a.in[12] + (size_t)l * DM;
;             const int kb = r / (DM / 32), nb = r % (DM / 32);
;             bf16_t* WT = (bf16_t*)(ws + WS_WOUT + (size_t)l * SZ_WOUT);
;             tr_item(W, DM, 32 * nb, 64 * kb, gain, WT, DM, 32 * nb, scr, lane);
.LBB0_29:
	s_mul_hi_i32 s8, s84, 0x6bca1af3
	s_lshr_b32 s18, s8, 31
	s_ashr_i32 s8, s8, 13
	s_add_i32 s18, s8, s18
	s_mul_i32 s8, s18, 0xffffb400
	s_add_i32 s85, s84, s8
	s_cmpk_gt_i32 s85, 0x2bff
	s_mov_b64 s[20:21], -1
	s_cbranch_scc0 .LBB0_44
	s_ashr_i32 s19, s18, 31
	s_cmpk_gt_u32 s85, 0x43ff
	s_cbranch_scc0 .LBB0_34
	s_lshl_b64 s[20:21], s[18:19], 24
	s_add_u32 s88, s6, s20
	s_addc_u32 s89, s7, s21
	s_and_b32 s20, s85, 0x7fffffc0
	s_addk_i32 s20, 0xbc00
	v_or_b32_e32 v2, s20, v5
	s_and_b32 s86, s35, 0x7e0
	v_lshlrev_b64 v[8:9], 13, v[2:3]
	v_lshl_add_u64 v[8:9], s[88:89], 0, v[8:9]
	s_lshl_b32 s8, s86, 2
	v_lshl_add_u64 v[8:9], v[8:9], 0, s[8:9]
	v_mov_b32_e32 v7, v3
	v_lshl_add_u64 v[32:33], v[8:9], 0, v[6:7]
	v_add_co_u32_e32 v10, vcc, s37, v32
	s_nop 1
	v_addc_co_u32_e32 v11, vcc, 0, v33, vcc
	v_add_co_u32_e32 v12, vcc, s38, v32
	s_nop 1
	v_addc_co_u32_e32 v13, vcc, 0, v33, vcc
	v_add_co_u32_e32 v14, vcc, s39, v32
	s_nop 1
	v_addc_co_u32_e32 v15, vcc, 0, v33, vcc
	v_add_co_u32_e32 v16, vcc, s40, v32
	s_nop 1
	v_addc_co_u32_e32 v17, vcc, 0, v33, vcc
	v_add_co_u32_e32 v18, vcc, s41, v32
	s_nop 1
	v_addc_co_u32_e32 v19, vcc, 0, v33, vcc
	v_add_co_u32_e32 v20, vcc, s42, v32
	s_nop 1
	v_addc_co_u32_e32 v21, vcc, 0, v33, vcc
	v_add_co_u32_e32 v22, vcc, s43, v32
	s_nop 1
	v_addc_co_u32_e32 v23, vcc, 0, v33, vcc
	global_load_dword v8, v[32:33], off nt
	global_load_dword v9, v[10:11], off nt
	s_nop 0
	global_load_dword v12, v[12:13], off nt
	s_nop 0
	global_load_dword v13, v[14:15], off nt
	global_load_dword v10, v[16:17], off nt
	global_load_dword v11, v[18:19], off nt
	s_nop 0
	global_load_dword v14, v[20:21], off nt
	global_load_dword v15, v[22:23], off nt
	v_add_co_u32_e32 v16, vcc, s44, v32
	s_nop 1
	v_addc_co_u32_e32 v17, vcc, 0, v33, vcc
	v_add_co_u32_e32 v18, vcc, s45, v32
	s_nop 1
	v_addc_co_u32_e32 v19, vcc, 0, v33, vcc
	v_add_co_u32_e32 v20, vcc, s46, v32
	s_nop 1
	v_addc_co_u32_e32 v21, vcc, 0, v33, vcc
	v_add_co_u32_e32 v22, vcc, s47, v32
	s_nop 1
	v_addc_co_u32_e32 v23, vcc, 0, v33, vcc
	v_add_co_u32_e32 v24, vcc, s48, v32
	s_nop 1
	v_addc_co_u32_e32 v25, vcc, 0, v33, vcc
	v_add_co_u32_e32 v26, vcc, s49, v32
	s_nop 1
	v_addc_co_u32_e32 v27, vcc, 0, v33, vcc
	v_add_co_u32_e32 v28, vcc, s50, v32
	s_nop 1
	v_addc_co_u32_e32 v29, vcc, 0, v33, vcc
	v_add_co_u32_e32 v30, vcc, s51, v32
	s_nop 1
	v_addc_co_u32_e32 v31, vcc, 0, v33, vcc
	global_load_dword v16, v[16:17], off nt
	s_nop 0
	global_load_dword v17, v[18:19], off nt
	s_nop 0
	global_load_dword v20, v[20:21], off nt
	s_nop 0
	global_load_dword v21, v[22:23], off nt
	global_load_dword v18, v[24:25], off nt
	global_load_dword v19, v[26:27], off nt
	s_nop 0
	global_load_dword v22, v[28:29], off nt
	global_load_dword v23, v[30:31], off nt
	v_add_co_u32_e32 v24, vcc, s52, v32
	s_nop 1
	v_addc_co_u32_e32 v25, vcc, 0, v33, vcc
	v_add_co_u32_e32 v26, vcc, s53, v32
	s_nop 1
	v_addc_co_u32_e32 v27, vcc, 0, v33, vcc
	v_add_co_u32_e32 v28, vcc, s54, v32
	s_nop 1
	v_addc_co_u32_e32 v29, vcc, 0, v33, vcc
	v_add_co_u32_e32 v30, vcc, s55, v32
	s_nop 1
	v_addc_co_u32_e32 v31, vcc, 0, v33, vcc
	v_add_co_u32_e32 v34, vcc, s56, v32
	s_nop 1
	v_addc_co_u32_e32 v35, vcc, 0, v33, vcc
	v_add_co_u32_e32 v36, vcc, s57, v32
	s_nop 1
	v_addc_co_u32_e32 v37, vcc, 0, v33, vcc
	v_add_co_u32_e32 v38, vcc, s58, v32
	s_nop 1
	v_addc_co_u32_e32 v39, vcc, 0, v33, vcc
	v_add_co_u32_e32 v46, vcc, s59, v32
	s_nop 1
	v_addc_co_u32_e32 v47, vcc, 0, v33, vcc
	global_load_dword v24, v[24:25], off nt
	s_nop 0
	global_load_dword v25, v[26:27], off nt
	s_nop 0
	global_load_dword v28, v[28:29], off nt
	s_nop 0
	global_load_dword v29, v[30:31], off nt
	global_load_dword v26, v[34:35], off nt
	global_load_dword v27, v[36:37], off nt
	s_nop 0
	global_load_dword v30, v[38:39], off nt
	global_load_dword v31, v[46:47], off nt
	v_add_co_u32_e32 v34, vcc, s60, v32
	s_nop 1
	v_addc_co_u32_e32 v35, vcc, 0, v33, vcc
	v_add_co_u32_e32 v36, vcc, s61, v32
	s_nop 1
	v_addc_co_u32_e32 v37, vcc, 0, v33, vcc
	v_add_co_u32_e32 v38, vcc, s62, v32
	s_nop 1
	v_addc_co_u32_e32 v39, vcc, 0, v33, vcc
	v_add_co_u32_e32 v46, vcc, s63, v32
	s_nop 1
	v_addc_co_u32_e32 v47, vcc, 0, v33, vcc
	v_add_co_u32_e32 v48, vcc, s64, v32
	s_nop 1
	v_addc_co_u32_e32 v49, vcc, 0, v33, vcc
	v_add_co_u32_e32 v50, vcc, 0x74000, v32
	s_nop 1
	v_addc_co_u32_e32 v51, vcc, 0, v33, vcc
	v_add_co_u32_e32 v52, vcc, 0x78000, v32
	s_nop 1
	v_addc_co_u32_e32 v53, vcc, 0, v33, vcc
	v_add_co_u32_e32 v54, vcc, 0x7c000, v32
	s_nop 1
	v_addc_co_u32_e32 v55, vcc, 0, v33, vcc
	global_load_dword v32, v[34:35], off nt
	global_load_dword v33, v[36:37], off nt
	s_nop 0
	global_load_dword v38, v[38:39], off nt
	s_nop 0
	global_load_dword v39, v[46:47], off nt
	global_load_dword v36, v[48:49], off nt
	global_load_dword v37, v[50:51], off nt
	global_load_dword v34, v[52:53], off nt
	global_load_dword v35, v[54:55], off nt
	s_andn2_b64 vcc, exec, s[10:11]
	s_cbranch_vccnz .LBB0_33
; __device__ __forceinline__ void tr_item(const float* W, int ldw, int src_col0, int k0, const float* gain, bf16_t* WT, int K, int dst_row0, LAS float* scr, int lane) {
;     ...
;     if (gain) {
; #pragma unroll
;         for (int i = 0; i < 32; ++i) v[i] *= gain[k0 + 2 * i + (lane >> 5)]; }
	s_lshl_b64 s[88:89], s[18:19], 13
	s_add_u32 s88, s4, s88
	s_addc_u32 s89, s5, s89
	v_lshl_add_u64 v[46:47], v[2:3], 2, s[88:89]
	global_load_dword v48, v[46:47], off nt
	global_load_dword v49, v[46:47], off offset:8 nt
	global_load_dword v50, v[46:47], off offset:16 nt
	global_load_dword v51, v[46:47], off offset:24 nt
	global_load_dword v52, v[46:47], off offset:32 nt
	global_load_dword v53, v[46:47], off offset:40 nt
	global_load_dword v54, v[46:47], off offset:48 nt
	global_load_dword v55, v[46:47], off offset:56 nt
	global_load_dword v56, v[46:47], off offset:64 nt
	global_load_dword v57, v[46:47], off offset:72 nt
	global_load_dword v58, v[46:47], off offset:80 nt
	global_load_dword v59, v[46:47], off offset:88 nt
	global_load_dword v60, v[46:47], off offset:96 nt
	global_load_dword v61, v[46:47], off offset:104 nt
	global_load_dword v62, v[46:47], off offset:112 nt
	global_load_dword v63, v[46:47], off offset:120 nt
	global_load_dword v64, v[46:47], off offset:128 nt
	global_load_dword v65, v[46:47], off offset:136 nt
	global_load_dword v66, v[46:47], off offset:144 nt
	global_load_dword v67, v[46:47], off offset:152 nt
	global_load_dword v68, v[46:47], off offset:160 nt
	global_load_dword v69, v[46:47], off offset:168 nt
	global_load_dword v70, v[46:47], off offset:176 nt
	global_load_dword v71, v[46:47], off offset:184 nt
	global_load_dword v72, v[46:47], off offset:192 nt
	global_load_dword v73, v[46:47], off offset:200 nt
	global_load_dword v74, v[46:47], off offset:208 nt
	global_load_dword v75, v[46:47], off offset:216 nt
	global_load_dword v76, v[46:47], off offset:224 nt
	global_load_dword v77, v[46:47], off offset:232 nt
	global_load_dword v78, v[46:47], off offset:240 nt
	global_load_dword v79, v[46:47], off offset:248 nt
	s_waitcnt vmcnt(30)
	v_pk_mul_f32 v[8:9], v[8:9], v[48:49]
	s_waitcnt vmcnt(28)
	v_pk_mul_f32 v[12:13], v[12:13], v[50:51]
	s_waitcnt vmcnt(26)
	v_pk_mul_f32 v[10:11], v[10:11], v[52:53]
	s_waitcnt vmcnt(24)
	v_pk_mul_f32 v[14:15], v[14:15], v[54:55]
	s_waitcnt vmcnt(22)
	v_pk_mul_f32 v[16:17], v[16:17], v[56:57]
	s_waitcnt vmcnt(20)
	v_pk_mul_f32 v[20:21], v[20:21], v[58:59]
	s_waitcnt vmcnt(18)
	v_pk_mul_f32 v[18:19], v[18:19], v[60:61]
	s_waitcnt vmcnt(16)
	v_pk_mul_f32 v[22:23], v[22:23], v[62:63]
	s_waitcnt vmcnt(14)
	v_pk_mul_f32 v[24:25], v[24:25], v[64:65]
	s_waitcnt vmcnt(12)
	v_pk_mul_f32 v[28:29], v[28:29], v[66:67]
	s_waitcnt vmcnt(10)
	v_pk_mul_f32 v[26:27], v[26:27], v[68:69]
	s_waitcnt vmcnt(8)
	v_pk_mul_f32 v[30:31], v[30:31], v[70:71]
	s_waitcnt vmcnt(6)
	v_pk_mul_f32 v[32:33], v[32:33], v[72:73]
	s_waitcnt vmcnt(4)
	v_pk_mul_f32 v[38:39], v[38:39], v[74:75]
	s_waitcnt vmcnt(2)
	v_pk_mul_f32 v[36:37], v[36:37], v[76:77]
	s_waitcnt vmcnt(0)
	v_pk_mul_f32 v[34:35], v[34:35], v[78:79]

; __device__ __forceinline__ void tr_item(const float* W, int ldw, int src_col0, int k0, const float* gain, bf16_t* WT, int K, int dst_row0, LAS float* scr, int lane) {
;     ...
;     const float* wp = W + (size_t)(k0 + (lane >> 5)) * ldw + src_col0 + (lane & 31);
; #pragma unroll
;     for (int i = 0; i < 32; ++i) v[i] = wp[(size_t)(2 * i) * ldw];
; __device__ __forceinline__ void prologue(const Args& a, unsigned char* ws, LAS unsigned char* lds, int gw, int ngw, int wave, int lane) {
;     ...
;         } else if (r < 2 * IT_D + IT_WIN) {
;             r -= 2 * IT_D;
;             const float* W = a.in[6] + (size_t)l * DM * INCOLS; const float* gain = a.in[5] + (size_t)l * DM;
;             const int kb = r / (NWIN / 32), db = r % (NWIN / 32);
;             bf16_t* WT = (bf16_t*)(ws + WS_WIN + (size_t)l * SZ_WIN);
;             tr_item(W, INCOLS, win_src_col(db), 64 * kb, gain, WT, DM, 32 * db, scr, lane);
.LBB0_40:
	s_mul_i32 s20, s18, 0x3010000
	s_mul_hi_i32 s21, s18, 0x3010000
	s_add_u32 s20, s14, s20
	s_addc_u32 s21, s15, s21
	s_lshl_b32 s89, s87, 6
	s_and_b32 s89, s89, 0x7fc0
	v_or_b32_e32 v2, s89, v5
	v_mov_b64_e32 v[8:9], s[20:21]
	s_movk_i32 s20, 0x6020
	v_mad_u64_u32 v[8:9], s[20:21], v2, s20, v[8:9]
	v_lshl_add_u64 v[8:9], s[8:9], 2, v[8:9]
	v_mov_b32_e32 v7, v3
	v_lshl_add_u64 v[32:33], v[8:9], 0, v[6:7]
	v_add_co_u32_e32 v10, vcc, s39, v32
	s_mov_b32 s8, 0x84000
	s_nop 0
	v_addc_co_u32_e32 v11, vcc, 0, v33, vcc
	v_add_co_u32_e32 v12, vcc, s42, v32
	s_nop 1
	v_addc_co_u32_e32 v13, vcc, 0, v33, vcc
	v_add_co_u32_e32 v14, vcc, s45, v32
	s_nop 1
	v_addc_co_u32_e32 v15, vcc, 0, v33, vcc
	v_add_co_u32_e32 v16, vcc, s48, v32
	s_nop 1
	v_addc_co_u32_e32 v17, vcc, 0, v33, vcc
	v_add_co_u32_e32 v18, vcc, s51, v32
	s_nop 1
	v_addc_co_u32_e32 v19, vcc, 0, v33, vcc
	v_add_co_u32_e32 v20, vcc, s54, v32
	s_nop 1
	v_addc_co_u32_e32 v21, vcc, 0, v33, vcc
	v_add_co_u32_e32 v22, vcc, s57, v32
	s_nop 1
	v_addc_co_u32_e32 v23, vcc, 0, v33, vcc
	global_load_dword v8, v[32:33], off nt
	global_load_dword v9, v[10:11], off offset:64 nt
	s_nop 0
	global_load_dword v12, v[12:13], off offset:128 nt
	s_nop 0
	global_load_dword v13, v[14:15], off offset:192 nt
	global_load_dword v10, v[16:17], off offset:256 nt
	global_load_dword v11, v[18:19], off offset:320 nt
	s_nop 0
	global_load_dword v14, v[20:21], off offset:384 nt
	global_load_dword v15, v[22:23], off offset:448 nt
	v_add_co_u32_e32 v16, vcc, s60, v32
	s_nop 1
	v_addc_co_u32_e32 v17, vcc, 0, v33, vcc
	v_add_co_u32_e32 v18, vcc, s63, v32
	s_nop 1
	v_addc_co_u32_e32 v19, vcc, 0, v33, vcc
	v_add_co_u32_e32 v20, vcc, s65, v32
	s_nop 1
	v_addc_co_u32_e32 v21, vcc, 0, v33, vcc
	v_add_co_u32_e32 v22, vcc, s8, v32
	s_mov_b32 s8, 0x90000
	s_nop 0
	v_addc_co_u32_e32 v23, vcc, 0, v33, vcc
	v_add_co_u32_e32 v24, vcc, s8, v32
	s_nop 1
	v_addc_co_u32_e32 v25, vcc, 0, v33, vcc
	v_add_co_u32_e32 v26, vcc, s68, v32
	s_nop 1
	v_addc_co_u32_e32 v27, vcc, 0, v33, vcc
	v_add_co_u32_e32 v28, vcc, s69, v32
	s_nop 1
	v_addc_co_u32_e32 v29, vcc, 0, v33, vcc
	v_add_co_u32_e32 v30, vcc, s70, v32
	s_nop 1
	v_addc_co_u32_e32 v31, vcc, 0, v33, vcc
	global_load_dword v16, v[16:17], off offset:512 nt
	s_nop 0
	global_load_dword v17, v[18:19], off offset:576 nt
	s_nop 0
	global_load_dword v20, v[20:21], off offset:640 nt
	s_nop 0
	global_load_dword v21, v[22:23], off offset:704 nt
	global_load_dword v18, v[24:25], off offset:768 nt
	global_load_dword v19, v[26:27], off offset:832 nt
	s_nop 0
	global_load_dword v22, v[28:29], off offset:896 nt
	global_load_dword v23, v[30:31], off offset:960 nt
	v_add_co_u32_e32 v24, vcc, s71, v32
	s_nop 1
	v_addc_co_u32_e32 v25, vcc, 0, v33, vcc
	v_add_co_u32_e32 v26, vcc, s72, v32
	s_nop 1
	v_addc_co_u32_e32 v27, vcc, 0, v33, vcc
	v_add_co_u32_e32 v28, vcc, s73, v32
	s_nop 1
	v_addc_co_u32_e32 v29, vcc, 0, v33, vcc
	v_add_co_u32_e32 v30, vcc, s74, v32
	s_nop 1
	v_addc_co_u32_e32 v31, vcc, 0, v33, vcc
	v_add_co_u32_e32 v34, vcc, s75, v32
	s_nop 1
	v_addc_co_u32_e32 v35, vcc, 0, v33, vcc
	v_add_co_u32_e32 v36, vcc, s76, v32
	s_nop 1
	v_addc_co_u32_e32 v37, vcc, 0, v33, vcc
	v_add_co_u32_e32 v38, vcc, s77, v32
	s_nop 1
	v_addc_co_u32_e32 v39, vcc, 0, v33, vcc
	v_add_co_u32_e32 v46, vcc, s78, v32
	s_nop 1
	v_addc_co_u32_e32 v47, vcc, 0, v33, vcc
	global_load_dword v24, v[24:25], off offset:1024 nt
	s_nop 0
	global_load_dword v25, v[26:27], off offset:1088 nt
	s_nop 0
	global_load_dword v28, v[28:29], off offset:1152 nt
	s_nop 0
	global_load_dword v29, v[30:31], off offset:1216 nt
	global_load_dword v26, v[34:35], off offset:1280 nt
	global_load_dword v27, v[36:37], off offset:1344 nt
	s_nop 0
	global_load_dword v30, v[38:39], off offset:1408 nt
	global_load_dword v31, v[46:47], off offset:1472 nt
	v_add_co_u32_e32 v34, vcc, s79, v32
	s_nop 1
	v_addc_co_u32_e32 v35, vcc, 0, v33, vcc
	v_add_co_u32_e32 v36, vcc, s80, v32
	s_nop 1
	v_addc_co_u32_e32 v37, vcc, 0, v33, vcc
	v_add_co_u32_e32 v38, vcc, s81, v32
	s_nop 1
	v_addc_co_u32_e32 v39, vcc, 0, v33, vcc
	v_add_co_u32_e32 v46, vcc, s82, v32
	s_nop 1
	v_addc_co_u32_e32 v47, vcc, 0, v33, vcc
	v_add_co_u32_e32 v48, vcc, s83, v32
	s_nop 1
	v_addc_co_u32_e32 v49, vcc, 0, v33, vcc
	v_add_co_u32_e32 v50, vcc, 0x15c000, v32
	s_nop 1
	v_addc_co_u32_e32 v51, vcc, 0, v33, vcc
	v_add_co_u32_e32 v52, vcc, 0x168000, v32
	s_nop 1
	v_addc_co_u32_e32 v53, vcc, 0, v33, vcc
	v_add_co_u32_e32 v54, vcc, 0x174000, v32
	s_nop 1
	v_addc_co_u32_e32 v55, vcc, 0, v33, vcc
	global_load_dword v32, v[34:35], off offset:1536 nt
	global_load_dword v33, v[36:37], off offset:1600 nt
	s_nop 0
	global_load_dword v38, v[38:39], off offset:1664 nt
	s_nop 0
	global_load_dword v39, v[46:47], off offset:1728 nt
	global_load_dword v36, v[48:49], off offset:1792 nt
	global_load_dword v37, v[50:51], off offset:1856 nt
	global_load_dword v34, v[52:53], off offset:1920 nt
	global_load_dword v35, v[54:55], off offset:1984 nt
	s_andn2_b64 vcc, exec, s[16:17]
	s_cbranch_vccnz .LBB0_42
; __device__ __forceinline__ void tr_item(const float* W, int ldw, int src_col0, int k0, const float* gain, bf16_t* WT, int K, int dst_row0, LAS float* scr, int lane) {
;     ...
;     if (gain) {
; #pragma unroll
;         for (int i = 0; i < 32; ++i) v[i] *= gain[k0 + 2 * i + (lane >> 5)]; }
	s_lshl_b64 s[20:21], s[18:19], 13
	s_add_u32 s20, s12, s20
	s_addc_u32 s21, s13, s21
	v_lshlrev_b32_e32 v2, 2, v2
	global_load_dword v46, v2, s[20:21] nt
	global_load_dword v47, v2, s[20:21] offset:8 nt
	global_load_dword v48, v2, s[20:21] offset:16 nt
	global_load_dword v49, v2, s[20:21] offset:24 nt
	global_load_dword v50, v2, s[20:21] offset:32 nt
	global_load_dword v51, v2, s[20:21] offset:40 nt
	global_load_dword v52, v2, s[20:21] offset:48 nt
	global_load_dword v53, v2, s[20:21] offset:56 nt
	global_load_dword v54, v2, s[20:21] offset:64 nt
	global_load_dword v55, v2, s[20:21] offset:72 nt
	global_load_dword v56, v2, s[20:21] offset:80 nt
	global_load_dword v57, v2, s[20:21] offset:88 nt
	global_load_dword v58, v2, s[20:21] offset:96 nt
	global_load_dword v59, v2, s[20:21] offset:104 nt
	global_load_dword v60, v2, s[20:21] offset:112 nt
	global_load_dword v61, v2, s[20:21] offset:120 nt
	global_load_dword v62, v2, s[20:21] offset:128 nt
	global_load_dword v63, v2, s[20:21] offset:136 nt
	global_load_dword v64, v2, s[20:21] offset:144 nt
	global_load_dword v65, v2, s[20:21] offset:152 nt
	global_load_dword v66, v2, s[20:21] offset:160 nt
	global_load_dword v67, v2, s[20:21] offset:168 nt
	global_load_dword v68, v2, s[20:21] offset:176 nt
	global_load_dword v69, v2, s[20:21] offset:184 nt
	global_load_dword v70, v2, s[20:21] offset:192 nt
	global_load_dword v71, v2, s[20:21] offset:200 nt
	global_load_dword v72, v2, s[20:21] offset:208 nt
	global_load_dword v73, v2, s[20:21] offset:216 nt
	global_load_dword v74, v2, s[20:21] offset:224 nt
	global_load_dword v75, v2, s[20:21] offset:232 nt
	global_load_dword v76, v2, s[20:21] offset:240 nt
	global_load_dword v77, v2, s[20:21] offset:248 nt
	s_waitcnt vmcnt(30)
	v_pk_mul_f32 v[8:9], v[8:9], v[46:47]
	s_waitcnt vmcnt(28)
	v_pk_mul_f32 v[12:13], v[12:13], v[48:49]
	s_waitcnt vmcnt(26)
	v_pk_mul_f32 v[10:11], v[10:11], v[50:51]
	s_waitcnt vmcnt(24)
	v_pk_mul_f32 v[14:15], v[14:15], v[52:53]
	s_waitcnt vmcnt(22)
	v_pk_mul_f32 v[16:17], v[16:17], v[54:55]
	s_waitcnt vmcnt(20)
	v_pk_mul_f32 v[20:21], v[20:21], v[56:57]
	s_waitcnt vmcnt(18)
	v_pk_mul_f32 v[18:19], v[18:19], v[58:59]
	s_waitcnt vmcnt(16)
	v_pk_mul_f32 v[22:23], v[22:23], v[60:61]
	s_waitcnt vmcnt(14)
	v_pk_mul_f32 v[24:25], v[24:25], v[62:63]
	s_waitcnt vmcnt(12)
	v_pk_mul_f32 v[28:29], v[28:29], v[64:65]
	s_waitcnt vmcnt(10)
	v_pk_mul_f32 v[26:27], v[26:27], v[66:67]
	s_waitcnt vmcnt(8)
	v_pk_mul_f32 v[30:31], v[30:31], v[68:69]
	s_waitcnt vmcnt(6)
	v_pk_mul_f32 v[32:33], v[32:33], v[70:71]
	s_waitcnt vmcnt(4)
	v_pk_mul_f32 v[38:39], v[38:39], v[72:73]
	s_waitcnt vmcnt(2)
	v_pk_mul_f32 v[36:37], v[36:37], v[74:75]
	s_waitcnt vmcnt(0)
	v_pk_mul_f32 v[34:35], v[34:35], v[76:77]

; __device__ __forceinline__ void tr_item(const float* W, int ldw, int src_col0, int k0, const float* gain, bf16_t* WT, int K, int dst_row0, LAS float* scr, int lane) {
;     ...
;     for (int i = 0; i < 32; ++i) scr[(2 * i + (lane >> 5)) * 33 + (lane & 31)] = v[i];
; __device__ __forceinline__ void prologue(const Args& a, unsigned char* ws, LAS unsigned char* lds, int gw, int ngw, int wave, int lane) {
;     ...
;         if (r < 2 * IT_D) {
;             const int f = r / IT_D; r -= f * IT_D;
;             const float* W = a.in[f ? 17 : 4] + (size_t)l * DFF * DM;
;             const int kb = r / (DM / 32), nb = r % (DM / 32);
;             bf16_t* WT = (bf16_t*)(ws + WS_WD + (size_t)(l * 2 + f) * SZ_WD);
;             tr_item(W, DM, 32 * nb, 64 * kb, nullptr, WT, DFF, 32 * nb, scr, lane);
.LBB0_45:
	s_mul_hi_i32 s8, s85, 0x2e8ba2e9
	s_lshr_b32 s19, s8, 31
	s_ashr_i32 s8, s8, 10
	s_add_i32 s19, s8, s19
	s_mul_i32 s8, s19, 0xffffea00
	s_add_i32 s88, s85, s8
	s_addk_i32 s85, 0x15ff
	s_cmpk_lt_u32 s85, 0x2bff
	s_cselect_b32 s8, 32, 0x88
	s_add_u32 s20, s92, s8
	s_addc_u32 s21, s93, 0
	s_load_dwordx2 s[20:21], s[20:21], 0x0
	s_mul_i32 s86, s18, 0x1600
	s_ashr_i32 s87, s86, 31
	s_lshl_b64 s[86:87], s[86:87], 13
	v_mov_b32_e32 v7, v3
	s_waitcnt lgkmcnt(0)
	s_add_u32 s86, s20, s86
	s_addc_u32 s87, s21, s87
	s_ashr_i32 s8, s88, 31
	s_lshr_b32 s8, s8, 26
	s_add_i32 s20, s88, s8
	s_lshl_b32 s18, s18, 1
	s_and_b32 s89, s20, 0xffffffc0
	s_add_i32 s18, s19, s18
	s_ashr_i32 s8, s20, 6
	s_sub_i32 s85, s88, s89
	s_mul_hi_i32 s19, s18, 0x1600000
	s_mul_i32 s18, s18, 0x1600000
	v_or_b32_e32 v8, s89, v5
	s_add_u32 s20, s31, s18
	v_ashrrev_i32_e32 v9, 31, v8
	s_addc_u32 s21, s34, s19
	s_lshl_b32 s18, s85, 5
	v_lshlrev_b64 v[8:9], 13, v[8:9]
	v_lshl_add_u64 v[8:9], s[86:87], 0, v[8:9]
	s_ashr_i32 s19, s18, 31
	v_lshl_add_u64 v[8:9], s[18:19], 2, v[8:9]
	v_lshl_add_u64 v[8:9], v[8:9], 0, v[6:7]
	v_add_co_u32_e32 v10, vcc, s37, v8
	s_mov_b32 s19, 0x74000
	s_nop 0
	v_addc_co_u32_e32 v11, vcc, 0, v9, vcc
	v_add_co_u32_e32 v12, vcc, s38, v8
	s_nop 1
	v_addc_co_u32_e32 v13, vcc, 0, v9, vcc
	v_add_co_u32_e32 v14, vcc, s39, v8
	s_nop 1
	v_addc_co_u32_e32 v15, vcc, 0, v9, vcc
	v_add_co_u32_e32 v16, vcc, s40, v8
	s_nop 1
	v_addc_co_u32_e32 v17, vcc, 0, v9, vcc
	v_add_co_u32_e32 v18, vcc, s41, v8
	s_nop 1
	v_addc_co_u32_e32 v19, vcc, 0, v9, vcc
	v_add_co_u32_e32 v20, vcc, s42, v8
	s_nop 1
	v_addc_co_u32_e32 v21, vcc, 0, v9, vcc
	v_add_co_u32_e32 v22, vcc, s43, v8
	s_nop 1
	v_addc_co_u32_e32 v23, vcc, 0, v9, vcc
	global_load_dword v2, v[8:9], off nt
	global_load_dword v7, v[10:11], off nt
	global_load_dword v26, v[12:13], off nt
	global_load_dword v27, v[14:15], off nt
	global_load_dword v28, v[16:17], off nt
	global_load_dword v29, v[18:19], off nt
	global_load_dword v30, v[20:21], off nt
	global_load_dword v31, v[22:23], off nt
	v_add_co_u32_e32 v10, vcc, s44, v8
	s_nop 1
	v_addc_co_u32_e32 v11, vcc, 0, v9, vcc
	v_add_co_u32_e32 v12, vcc, s45, v8
	s_nop 1
	v_addc_co_u32_e32 v13, vcc, 0, v9, vcc
	v_add_co_u32_e32 v14, vcc, s46, v8
	s_nop 1
	v_addc_co_u32_e32 v15, vcc, 0, v9, vcc
	v_add_co_u32_e32 v16, vcc, s47, v8
	s_nop 1
	v_addc_co_u32_e32 v17, vcc, 0, v9, vcc
	v_add_co_u32_e32 v18, vcc, s48, v8
	s_nop 1
	v_addc_co_u32_e32 v19, vcc, 0, v9, vcc
	v_add_co_u32_e32 v20, vcc, s49, v8
	s_nop 1
	v_addc_co_u32_e32 v21, vcc, 0, v9, vcc
	v_add_co_u32_e32 v22, vcc, s50, v8
	s_nop 1
	v_addc_co_u32_e32 v23, vcc, 0, v9, vcc
	v_add_co_u32_e32 v24, vcc, s51, v8
	s_nop 1
	v_addc_co_u32_e32 v25, vcc, 0, v9, vcc
	global_load_dword v32, v[10:11], off nt
	global_load_dword v33, v[12:13], off nt
	global_load_dword v34, v[14:15], off nt
	global_load_dword v35, v[16:17], off nt
	global_load_dword v36, v[18:19], off nt
	global_load_dword v37, v[20:21], off nt
	global_load_dword v38, v[22:23], off nt
	global_load_dword v39, v[24:25], off nt
	v_add_co_u32_e32 v10, vcc, s52, v8
	s_nop 1
	v_addc_co_u32_e32 v11, vcc, 0, v9, vcc
	v_add_co_u32_e32 v12, vcc, s53, v8
	s_nop 1
	v_addc_co_u32_e32 v13, vcc, 0, v9, vcc
	v_add_co_u32_e32 v14, vcc, s54, v8
	s_nop 1
	v_addc_co_u32_e32 v15, vcc, 0, v9, vcc
	v_add_co_u32_e32 v16, vcc, s55, v8
	s_nop 1
	v_addc_co_u32_e32 v17, vcc, 0, v9, vcc
	v_add_co_u32_e32 v18, vcc, s56, v8
	s_nop 1
	v_addc_co_u32_e32 v19, vcc, 0, v9, vcc
	v_add_co_u32_e32 v20, vcc, s57, v8
	s_nop 1
	v_addc_co_u32_e32 v21, vcc, 0, v9, vcc
	v_add_co_u32_e32 v22, vcc, s58, v8
	s_nop 1
	v_addc_co_u32_e32 v23, vcc, 0, v9, vcc
	v_add_co_u32_e32 v24, vcc, s59, v8
	s_nop 1
	v_addc_co_u32_e32 v25, vcc, 0, v9, vcc
	global_load_dword v46, v[10:11], off nt
	global_load_dword v47, v[12:13], off nt
	global_load_dword v48, v[14:15], off nt
	global_load_dword v49, v[16:17], off nt
	global_load_dword v50, v[18:19], off nt
	global_load_dword v51, v[20:21], off nt
	global_load_dword v52, v[22:23], off nt
	s_nop 0
	global_load_dword v24, v[24:25], off nt
	v_add_co_u32_e32 v10, vcc, s60, v8
	s_nop 1
	v_addc_co_u32_e32 v11, vcc, 0, v9, vcc
	v_add_co_u32_e32 v12, vcc, s61, v8
	s_nop 1
	v_addc_co_u32_e32 v13, vcc, 0, v9, vcc
	v_add_co_u32_e32 v14, vcc, s62, v8
	s_nop 1
	v_addc_co_u32_e32 v15, vcc, 0, v9, vcc
	v_add_co_u32_e32 v16, vcc, s63, v8
	s_nop 1
	v_addc_co_u32_e32 v17, vcc, 0, v9, vcc
	v_add_co_u32_e32 v18, vcc, s64, v8
	s_nop 1
	v_addc_co_u32_e32 v19, vcc, 0, v9, vcc
	v_add_co_u32_e32 v20, vcc, s19, v8
	s_mov_b32 s19, 0x7c000
	s_nop 0
	v_addc_co_u32_e32 v21, vcc, 0, v9, vcc
	v_add_co_u32_e32 v22, vcc, s65, v8
	s_nop 1
	v_addc_co_u32_e32 v23, vcc, 0, v9, vcc
	v_add_co_u32_e32 v8, vcc, s19, v8
	s_lshr_b32 s19, s85, 3
	s_nop 0
	v_addc_co_u32_e32 v9, vcc, 0, v9, vcc
	global_load_dword v10, v[10:11], off nt
	s_nop 0
	global_load_dword v11, v[12:13], off nt
	s_nop 0
	global_load_dword v12, v[14:15], off nt
	global_load_dword v13, v[16:17], off nt
	s_nop 0
	global_load_dword v14, v[18:19], off nt
	global_load_dword v15, v[20:21], off nt
	global_load_dword v16, v[22:23], off nt
	s_nop 0
	global_load_dword v8, v[8:9], off nt
	s_waitcnt vmcnt(30)
	ds_write2_b32 v40, v2, v7 offset1:66
	s_waitcnt vmcnt(28)
	ds_write2_b32 v40, v26, v27 offset0:132 offset1:198
	v_add_u32_e32 v2, 0x400, v40
	s_waitcnt vmcnt(26)
	ds_write2_b32 v2, v28, v29 offset0:8 offset1:74
	s_waitcnt vmcnt(24)
	ds_write2_b32 v2, v30, v31 offset0:140 offset1:206
	v_add_u32_e32 v2, 0x800, v40
	s_waitcnt vmcnt(22)
	ds_write2_b32 v2, v32, v33 offset0:16 offset1:82
	s_waitcnt vmcnt(20)
	ds_write2_b32 v2, v34, v35 offset0:148 offset1:214
	v_add_u32_e32 v2, 0xc00, v40
	s_waitcnt vmcnt(18)
; #define LAS __attribute__((address_space(3)))
; __device__ __forceinline__ unsigned pk2(float lo, float hi) { return f2bf(lo) | (f2bf(hi) << 16); }
; #define LDS_WAIT() asm volatile("s_waitcnt lgkmcnt(0)" ::: "memory")
; __device__ __forceinline__ void tr_item(const float* W, int ldw, int src_col0, int k0, const float* gain, bf16_t* WT, int K, int dst_row0, LAS float* scr, int lane) {
;     ...
;     for (int i = 0; i < 32; ++i) scr[(2 * i + (lane >> 5)) * 33 + (lane & 31)] = v[i];
;     LDS_WAIT(); asm volatile("" ::: "memory");
;     const int c = lane & 7;
; #pragma unroll
;     for (int j = 0; j < 4; ++j) { const int n = (lane >> 3) + 8 * j; const LAS float* s = scr + (8 * c) * 33 + n;
;         u32x4 o; o.x = pk2(s[0 * 33], s[1 * 33]); o.y = pk2(s[2 * 33], s[3 * 33]); o.z = pk2(s[4 * 33], s[5 * 33]); o.w = pk2(s[6 * 33], s[7 * 33]);
;         const int nn = dst_row0 + n;
;         *(u32x4*)(WT + ((size_t)(nn >> 8) * (K >> 6) + (k0 >> 6)) * (256 * 64) + (size_t)(nn & 255) * 64 + 8 * c) = o; }
;     LDS_WAIT(); asm volatile("" ::: "memory");
	ds_write2_b32 v2, v36, v37 offset0:24 offset1:90
	s_waitcnt vmcnt(16)
	ds_write2_b32 v2, v38, v39 offset0:156 offset1:222
	v_add_u32_e32 v2, 0x1000, v40
	s_waitcnt vmcnt(14)
	ds_write2_b32 v2, v46, v47 offset0:32 offset1:98
	s_waitcnt vmcnt(12)
	ds_write2_b32 v2, v48, v49 offset0:164 offset1:230
	v_add_u32_e32 v2, 0x1400, v40
	s_waitcnt vmcnt(10)
	ds_write2_b32 v2, v50, v51 offset0:40 offset1:106
	s_waitcnt vmcnt(8)
	ds_write2_b32 v2, v52, v24 offset0:172 offset1:238
	v_add_u32_e32 v2, 0x1800, v40
	s_waitcnt vmcnt(6)
	ds_write2_b32 v2, v10, v11 offset0:48 offset1:114
	s_waitcnt vmcnt(4)
	ds_write2_b32 v2, v12, v13 offset0:180 offset1:246
	v_add_u32_e32 v2, 0x1c00, v40
	s_waitcnt vmcnt(2)
	ds_write2_b32 v2, v14, v15 offset0:56 offset1:122
	s_waitcnt vmcnt(0)
	ds_write2_b32 v2, v16, v8 offset0:188 offset1:254
	s_waitcnt lgkmcnt(0)
	ds_read2_b32 v[12:13], v42 offset1:8
	ds_read2_b32 v[14:15], v42 offset0:33 offset1:41
	ds_read2_b32 v[16:17], v42 offset0:66 offset1:74
	ds_read2_b32 v[18:19], v42 offset0:99 offset1:107
	ds_read2_b32 v[20:21], v42 offset0:132 offset1:140
	s_waitcnt lgkmcnt(4)
	v_bfe_u32 v2, v12, 16, 1
	v_add3_u32 v2, v12, v2, s66
	s_waitcnt lgkmcnt(3)
	v_bfe_u32 v7, v14, 16, 1
	v_lshrrev_b32_e32 v2, 16, v2
	v_add3_u32 v7, v14, v7, s66
	ds_read2_b32 v[22:23], v42 offset0:165 offset1:173
	v_and_or_b32 v8, v7, s67, v2
	s_waitcnt lgkmcnt(3)
	v_bfe_u32 v2, v16, 16, 1
	v_add3_u32 v2, v16, v2, s66
	s_waitcnt lgkmcnt(2)
	v_bfe_u32 v7, v18, 16, 1
	ds_read2_b32 v[24:25], v42 offset0:198 offset1:206
	v_lshrrev_b32_e32 v2, 16, v2
	v_add3_u32 v7, v18, v7, s66
	ds_read2_b32 v[26:27], v42 offset0:231 offset1:239
	v_and_or_b32 v9, v7, s67, v2
	s_waitcnt lgkmcnt(3)
	v_bfe_u32 v2, v20, 16, 1
	v_add3_u32 v2, v20, v2, s66
	s_waitcnt lgkmcnt(2)
	v_bfe_u32 v7, v22, 16, 1
	v_lshrrev_b32_e32 v2, 16, v2
	v_add3_u32 v7, v22, v7, s66
	v_and_or_b32 v10, v7, s67, v2
	s_waitcnt lgkmcnt(1)
	v_bfe_u32 v2, v24, 16, 1
	s_mulk_i32 s19, 0x58
	v_add3_u32 v2, v24, v2, s66
	s_waitcnt lgkmcnt(0)
	v_bfe_u32 v7, v26, 16, 1
	s_add_i32 s86, s19, s8
	v_lshrrev_b32_e32 v2, 16, v2
	v_add3_u32 v7, v26, v7, s66
	s_ashr_i32 s87, s86, 31
	v_and_or_b32 v11, v7, s67, v2
	v_or_b32_e32 v2, s18, v41
	s_lshl_b64 s[86:87], s[86:87], 15
	s_add_u32 s20, s20, s86
	v_lshlrev_b32_e32 v2, 7, v2
	s_addc_u32 s21, s21, s87
	v_and_b32_e32 v2, 0x7380, v2
	v_lshl_add_u64 v[28:29], s[20:21], 0, v[2:3]
	v_lshlrev_b32_e32 v2, 1, v4
	v_lshl_add_u64 v[28:29], v[28:29], 0, v[2:3]
	v_bfe_u32 v7, v13, 16, 1
	global_store_dwordx4 v[28:29], v[8:11], off
	v_add3_u32 v7, v13, v7, s66
	v_lshrrev_b32_e32 v7, 16, v7
	v_bfe_u32 v8, v15, 16, 1
	v_add3_u32 v8, v15, v8, s66
	v_and_or_b32 v8, v8, s67, v7
	v_bfe_u32 v7, v17, 16, 1
	v_add3_u32 v7, v17, v7, s66
	v_bfe_u32 v9, v19, 16, 1
	v_lshrrev_b32_e32 v7, 16, v7
	v_add3_u32 v9, v19, v9, s66
	v_and_or_b32 v9, v9, s67, v7
	v_bfe_u32 v7, v21, 16, 1
	v_add3_u32 v7, v21, v7, s66
	v_bfe_u32 v10, v23, 16, 1
	v_lshrrev_b32_e32 v7, 16, v7
	v_add3_u32 v10, v23, v10, s66
	v_and_or_b32 v10, v10, s67, v7
	v_bfe_u32 v7, v25, 16, 1
	v_add3_u32 v7, v25, v7, s66
	v_bfe_u32 v11, v27, 16, 1
	v_lshrrev_b32_e32 v7, 16, v7
	v_add3_u32 v11, v27, v11, s66
	v_and_or_b32 v11, v11, s67, v7
	v_or_b32_e32 v7, s18, v43
	v_lshlrev_b32_e32 v7, 7, v7
	v_and_b32_e32 v12, 0x7780, v7
	v_mov_b32_e32 v13, v3
	v_lshl_add_u64 v[12:13], s[20:21], 0, v[12:13]
	ds_read2_b32 v[14:15], v42 offset0:16 offset1:24
	v_lshl_add_u64 v[12:13], v[12:13], 0, v[2:3]
	global_store_dwordx4 v[12:13], v[8:11], off
	ds_read2_b32 v[12:13], v42 offset0:49 offset1:57
	ds_read2_b32 v[16:17], v42 offset0:82 offset1:90
	ds_read2_b32 v[18:19], v42 offset0:115 offset1:123
	s_waitcnt lgkmcnt(3)
	v_bfe_u32 v7, v14, 16, 1
	v_add3_u32 v7, v14, v7, s66
	s_waitcnt lgkmcnt(2)
	v_bfe_u32 v8, v12, 16, 1
	ds_read2_b32 v[20:21], v42 offset0:148 offset1:156
	v_lshrrev_b32_e32 v7, 16, v7
	v_add3_u32 v8, v12, v8, s66
	ds_read2_b32 v[22:23], v42 offset0:181 offset1:189
	v_and_or_b32 v8, v8, s67, v7
	s_waitcnt lgkmcnt(3)
	v_bfe_u32 v7, v16, 16, 1
	v_add3_u32 v7, v16, v7, s66
	s_waitcnt lgkmcnt(2)
	v_bfe_u32 v9, v18, 16, 1
	ds_read2_b32 v[24:25], v42 offset0:214 offset1:222
	v_lshrrev_b32_e32 v7, 16, v7
	v_add3_u32 v9, v18, v9, s66
	ds_read2_b32 v[26:27], v42 offset0:247 offset1:255
	v_and_or_b32 v9, v9, s67, v7
	s_waitcnt lgkmcnt(3)
	v_bfe_u32 v7, v20, 16, 1
	v_add3_u32 v7, v20, v7, s66
	s_waitcnt lgkmcnt(2)
	v_bfe_u32 v10, v22, 16, 1
	v_lshrrev_b32_e32 v7, 16, v7
	v_add3_u32 v10, v22, v10, s66
	v_and_or_b32 v10, v10, s67, v7
	s_waitcnt lgkmcnt(1)
	v_bfe_u32 v7, v24, 16, 1
	v_add3_u32 v7, v24, v7, s66
	s_waitcnt lgkmcnt(0)
	v_bfe_u32 v11, v26, 16, 1
	v_lshrrev_b32_e32 v7, 16, v7
	v_add3_u32 v11, v26, v11, s66
	v_and_or_b32 v11, v11, s67, v7
	v_or_b32_e32 v7, s18, v44
	v_lshlrev_b32_e32 v7, 7, v7
	v_and_b32_e32 v28, 0x7b80, v7
	v_mov_b32_e32 v29, v3
	v_lshl_add_u64 v[28:29], s[20:21], 0, v[28:29]
	v_lshl_add_u64 v[28:29], v[28:29], 0, v[2:3]
	v_bfe_u32 v7, v15, 16, 1
	global_store_dwordx4 v[28:29], v[8:11], off
	v_add3_u32 v7, v15, v7, s66
	v_lshrrev_b32_e32 v7, 16, v7
	v_bfe_u32 v8, v13, 16, 1
	v_add3_u32 v8, v13, v8, s66
	v_and_or_b32 v8, v8, s67, v7
	v_bfe_u32 v7, v17, 16, 1
	v_add3_u32 v7, v17, v7, s66
	v_bfe_u32 v9, v19, 16, 1
	v_lshrrev_b32_e32 v7, 16, v7
	v_add3_u32 v9, v19, v9, s66
	v_and_or_b32 v9, v9, s67, v7
	v_bfe_u32 v7, v21, 16, 1
	v_add3_u32 v7, v21, v7, s66
	v_bfe_u32 v10, v23, 16, 1
	v_lshrrev_b32_e32 v7, 16, v7
	v_add3_u32 v10, v23, v10, s66
	v_and_or_b32 v10, v10, s67, v7
	v_bfe_u32 v7, v25, 16, 1
	v_add3_u32 v7, v25, v7, s66
	v_bfe_u32 v11, v27, 16, 1
	v_lshrrev_b32_e32 v7, 16, v7
	v_add3_u32 v11, v27, v11, s66
	v_and_or_b32 v11, v11, s67, v7
	v_or_b32_e32 v7, s18, v45
	v_lshlrev_b32_e32 v7, 7, v7
	v_and_b32_e32 v12, 0x7f80, v7
	v_mov_b32_e32 v13, v3
	v_lshl_add_u64 v[12:13], s[20:21], 0, v[12:13]
	v_lshl_add_u64 v[12:13], v[12:13], 0, v[2:3]
	global_store_dwordx4 v[12:13], v[8:11], off
	s_waitcnt lgkmcnt(0)
	s_branch .LBB0_28

; __device__ __forceinline__ unsigned pk2(float lo, float hi) { return f2bf(lo) | (f2bf(hi) << 16); }
; __device__ __forceinline__ void prologue(const Args& a, unsigned char* ws, LAS unsigned char* lds, int gw, int ngw, int wave, int lane) {
;     ...
;     {
;         const float* x = a.in[0]; bf16_t* xb = (bf16_t*)(ws + WS_XB); float* ssq = (float*)(ws + WS_SSQ);
;         for (int m = gw; m < MROWS; m += 2 * ngw) {
;             const int m2 = m + ngw; const bool has2 = m2 < MROWS;
;             const f32x4* xr0 = (const f32x4*)(x + (size_t)m * DM); const f32x4* xr1 = (const f32x4*)(x + (size_t)(has2 ? m2 : m) * DM);
;             f32x4 v[2][8];
; #pragma unroll
;             for (int j = 0; j < 4; ++j) { v[0][2 * j] = xr0[(j * 64 + lane) * 2]; v[0][2 * j + 1] = xr0[(j * 64 + lane) * 2 + 1]; v[1][2 * j] = xr1[(j * 64 + lane) * 2]; v[1][2 * j + 1] = xr1[(j * 64 + lane) * 2 + 1]; }
; #pragma unroll
;             for (int q = 0; q < 2; ++q) { if (q == 1 && !has2) break; const int mm = q ? m2 : m; float s = 0.f;
; #pragma unroll
;                 for (int j = 0; j < 4; ++j) { const f32x4 v0 = v[q][2 * j], v1 = v[q][2 * j + 1];
;                     s += (v0[0] * v0[0] + v0[1] * v0[1]) + (v0[2] * v0[2] + v0[3] * v0[3]) + (v1[0] * v1[0] + v1[1] * v1[1]) + (v1[2] * v1[2] + v1[3] * v1[3]);
;                     u32x4 w; w.x = pk2(v0[0], v0[1]); w.y = pk2(v0[2], v0[3]); w.z = pk2(v1[0], v1[1]); w.w = pk2(v1[2], v1[3]);
;                     *(u32x4*)(xb + (size_t)mm * DM + (j * 64 + lane) * 8) = w; }
.LBB0_50:
	s_ashr_i32 s17, s16, 31
	s_add_i32 s10, s16, s26
	s_lshl_b64 s[18:19], s[16:17], 13
	s_waitcnt lgkmcnt(0)
	s_add_u32 s18, s8, s18
	s_addc_u32 s19, s9, s19
	global_load_dwordx4 v[56:59], v52, s[18:19] nt
	global_load_dwordx4 v[60:63], v52, s[18:19] offset:16 nt
	global_load_dwordx4 v[64:67], v52, s[18:19] offset:2048 nt
	global_load_dwordx4 v[68:71], v52, s[18:19] offset:2064 nt
	global_load_dwordx4 v[72:75], v53, s[18:19] offset:16 nt
	global_load_dwordx4 v[76:79], v53, s[18:19] nt
	global_load_dwordx4 v[34:37], v54, s[18:19] offset:16 nt
	global_load_dwordx4 v[38:41], v54, s[18:19] nt
	s_cmpk_lt_i32 s10, 0x4000
	s_cselect_b64 s[18:19], -1, 0
	s_and_b64 s[20:21], s[18:19], exec
	s_cselect_b32 s20, s10, s16
	s_ashr_i32 s21, s20, 31
	s_lshl_b64 s[20:21], s[20:21], 13
	s_add_u32 s20, s8, s20
	s_addc_u32 s21, s9, s21
	global_load_dwordx4 v[26:29], v52, s[20:21] offset:16 nt
	global_load_dwordx4 v[30:33], v52, s[20:21] nt
	global_load_dwordx4 v[18:21], v52, s[20:21] offset:2064 nt
	global_load_dwordx4 v[22:25], v52, s[20:21] offset:2048 nt
	global_load_dwordx4 v[10:13], v53, s[20:21] offset:16 nt
	global_load_dwordx4 v[14:17], v53, s[20:21] nt
	global_load_dwordx4 v[2:5], v54, s[20:21] offset:16 nt
	global_load_dwordx4 v[6:9], v54, s[20:21] nt
	s_lshl_b64 s[28:29], s[16:17], 12
	v_lshl_add_u64 v[80:81], v[44:45], 0, s[28:29]
	s_waitcnt vmcnt(15)
	v_mul_f32_e32 v82, v57, v57
	v_mul_f32_e32 v83, v59, v59
	v_and_b32_sdwa v88, v59, v55 dst_sel:DWORD dst_unused:UNUSED_PAD src0_sel:WORD_1 src1_sel:DWORD
	v_and_b32_sdwa v89, v57, v55 dst_sel:DWORD dst_unused:UNUSED_PAD src0_sel:WORD_1 src1_sel:DWORD
	s_waitcnt vmcnt(14)
	v_and_b32_sdwa v92, v63, v55 dst_sel:DWORD dst_unused:UNUSED_PAD src0_sel:WORD_1 src1_sel:DWORD
	v_and_b32_sdwa v93, v61, v55 dst_sel:DWORD dst_unused:UNUSED_PAD src0_sel:WORD_1 src1_sel:DWORD
	s_waitcnt vmcnt(13)
	v_mul_f32_e32 v94, v65, v65
	v_mul_f32_e32 v95, v67, v67
	v_mul_f32_e32 v84, v61, v61
	v_mul_f32_e32 v85, v63, v63
	v_and_b32_sdwa v86, v58, v55 dst_sel:DWORD dst_unused:UNUSED_PAD src0_sel:WORD_1 src1_sel:DWORD
	v_and_b32_sdwa v87, v56, v55 dst_sel:DWORD dst_unused:UNUSED_PAD src0_sel:WORD_1 src1_sel:DWORD
	v_and_b32_sdwa v90, v62, v55 dst_sel:DWORD dst_unused:UNUSED_PAD src0_sel:WORD_1 src1_sel:DWORD
	v_and_b32_sdwa v91, v60, v55 dst_sel:DWORD dst_unused:UNUSED_PAD src0_sel:WORD_1 src1_sel:DWORD
	s_waitcnt vmcnt(12)
	v_mul_f32_e32 v96, v69, v69
	v_fmac_f32_e32 v82, v56, v56
	v_fmac_f32_e32 v83, v58, v58
	v_add3_u32 v59, v59, v88, s27
	v_add3_u32 v57, v57, v89, s27
	v_add3_u32 v63, v63, v92, s27
	v_add3_u32 v61, v61, v93, s27
	v_fmac_f32_e32 v94, v64, v64
	v_fmac_f32_e32 v95, v66, v66
	v_mul_f32_e32 v97, v71, v71
	v_fmac_f32_e32 v84, v60, v60
	v_fmac_f32_e32 v85, v62, v62
	v_add3_u32 v56, v56, v87, s27
	v_add3_u32 v58, v58, v86, s27
	v_add3_u32 v60, v60, v91, s27
	v_add3_u32 v62, v62, v90, s27
	v_fmac_f32_e32 v96, v68, v68
	v_add_f32_e32 v82, v82, v83
	v_and_b32_e32 v59, 0xffff0000, v59
	v_and_b32_e32 v83, 0xffff0000, v57
	v_and_b32_e32 v63, 0xffff0000, v63
	v_and_b32_e32 v61, 0xffff0000, v61
	v_add_f32_e32 v86, v94, v95
	v_fmac_f32_e32 v97, v70, v70
	v_add_f32_e32 v82, v82, v84
	v_or_b32_sdwa v57, v59, v58 dst_sel:DWORD dst_unused:UNUSED_PAD src0_sel:DWORD src1_sel:WORD_1
	v_or_b32_sdwa v56, v83, v56 dst_sel:DWORD dst_unused:UNUSED_PAD src0_sel:DWORD src1_sel:WORD_1
	v_or_b32_sdwa v59, v63, v62 dst_sel:DWORD dst_unused:UNUSED_PAD src0_sel:DWORD src1_sel:WORD_1
	v_or_b32_sdwa v58, v61, v60 dst_sel:DWORD dst_unused:UNUSED_PAD src0_sel:DWORD src1_sel:WORD_1
	v_add_f32_e32 v60, v86, v96
	v_add_f32_e32 v62, v85, v82
	global_store_dwordx4 v[80:81], v[56:59], off
	v_and_b32_sdwa v100, v67, v55 dst_sel:DWORD dst_unused:UNUSED_PAD src0_sel:WORD_1 src1_sel:DWORD
	v_and_b32_sdwa v101, v65, v55 dst_sel:DWORD dst_unused:UNUSED_PAD src0_sel:WORD_1 src1_sel:DWORD
	v_add_f32_e32 v56, v97, v60
	v_add_f32_e32 v56, v62, v56
	v_and_b32_sdwa v59, v71, v55 dst_sel:DWORD dst_unused:UNUSED_PAD src0_sel:WORD_1 src1_sel:DWORD
	v_and_b32_sdwa v62, v69, v55 dst_sel:DWORD dst_unused:UNUSED_PAD src0_sel:WORD_1 src1_sel:DWORD
	v_and_b32_sdwa v57, v70, v55 dst_sel:DWORD dst_unused:UNUSED_PAD src0_sel:WORD_1 src1_sel:DWORD
	v_and_b32_sdwa v58, v68, v55 dst_sel:DWORD dst_unused:UNUSED_PAD src0_sel:WORD_1 src1_sel:DWORD
	v_add3_u32 v59, v71, v59, s27
	v_add3_u32 v62, v69, v62, s27
	v_add3_u32 v58, v68, v58, s27
	v_add3_u32 v57, v70, v57, s27
	v_and_b32_e32 v59, 0xffff0000, v59
	v_and_b32_e32 v62, 0xffff0000, v62
	v_or_b32_sdwa v63, v59, v57 dst_sel:DWORD dst_unused:UNUSED_PAD src0_sel:DWORD src1_sel:WORD_1
	v_or_b32_sdwa v62, v62, v58 dst_sel:DWORD dst_unused:UNUSED_PAD src0_sel:DWORD src1_sel:WORD_1
	s_waitcnt vmcnt(11)
; __device__ __forceinline__ unsigned pk2(float lo, float hi) { return f2bf(lo) | (f2bf(hi) << 16); }
; __device__ __forceinline__ void prologue(const Args& a, unsigned char* ws, LAS unsigned char* lds, int gw, int ngw, int wave, int lane) {
;     ...
;             for (int q = 0; q < 2; ++q) { if (q == 1 && !has2) break; const int mm = q ? m2 : m; float s = 0.f;
; #pragma unroll
;                 for (int j = 0; j < 4; ++j) { const f32x4 v0 = v[q][2 * j], v1 = v[q][2 * j + 1];
;                     s += (v0[0] * v0[0] + v0[1] * v0[1]) + (v0[2] * v0[2] + v0[3] * v0[3]) + (v1[0] * v1[0] + v1[1] * v1[1]) + (v1[2] * v1[2] + v1[3] * v1[3]);
;                     u32x4 w; w.x = pk2(v0[0], v0[1]); w.y = pk2(v0[2], v0[3]); w.z = pk2(v1[0], v1[1]); w.w = pk2(v1[2], v1[3]);
;                     *(u32x4*)(xb + (size_t)mm * DM + (j * 64 + lane) * 8) = w; }
;                 s = wave_sum(s);
;                 if (lane < 32) ssq[(size_t)mm * 32 + lane] = lane == 0 ? s : 0.f; }
	v_mul_f32_e32 v57, v77, v77
	v_mul_f32_e32 v58, v79, v79
	v_fmac_f32_e32 v57, v76, v76
	v_fmac_f32_e32 v58, v78, v78
	v_add_f32_e32 v57, v57, v58
	v_mul_f32_e32 v58, v73, v73
	v_fmac_f32_e32 v58, v72, v72
	v_and_b32_sdwa v98, v66, v55 dst_sel:DWORD dst_unused:UNUSED_PAD src0_sel:WORD_1 src1_sel:DWORD
	v_and_b32_sdwa v99, v64, v55 dst_sel:DWORD dst_unused:UNUSED_PAD src0_sel:WORD_1 src1_sel:DWORD
	v_add3_u32 v67, v67, v100, s27
	v_add3_u32 v65, v65, v101, s27
	v_add_f32_e32 v57, v57, v58
	v_mul_f32_e32 v58, v75, v75
	v_add3_u32 v64, v64, v99, s27
	v_add3_u32 v66, v66, v98, s27
	v_and_b32_e32 v67, 0xffff0000, v67
	v_and_b32_e32 v65, 0xffff0000, v65
	v_fmac_f32_e32 v58, v74, v74
	v_or_b32_sdwa v61, v67, v66 dst_sel:DWORD dst_unused:UNUSED_PAD src0_sel:DWORD src1_sel:WORD_1
	v_or_b32_sdwa v60, v65, v64 dst_sel:DWORD dst_unused:UNUSED_PAD src0_sel:DWORD src1_sel:WORD_1
	v_add_f32_e32 v57, v58, v57
	global_store_dwordx4 v[80:81], v[60:63], off offset:1024
	v_and_b32_sdwa v59, v77, v55 dst_sel:DWORD dst_unused:UNUSED_PAD src0_sel:WORD_1 src1_sel:DWORD
	v_add3_u32 v59, v77, v59, s27
	v_add_f32_e32 v60, v56, v57
	v_and_b32_sdwa v57, v76, v55 dst_sel:DWORD dst_unused:UNUSED_PAD src0_sel:WORD_1 src1_sel:DWORD
	v_add3_u32 v58, v76, v57, s27
	v_and_b32_sdwa v57, v79, v55 dst_sel:DWORD dst_unused:UNUSED_PAD src0_sel:WORD_1 src1_sel:DWORD
	v_and_b32_sdwa v56, v78, v55 dst_sel:DWORD dst_unused:UNUSED_PAD src0_sel:WORD_1 src1_sel:DWORD
	v_add3_u32 v57, v79, v57, s27
	v_add3_u32 v56, v78, v56, s27
	v_and_b32_e32 v57, 0xffff0000, v57
	v_and_b32_e32 v59, 0xffff0000, v59
	v_or_b32_sdwa v57, v57, v56 dst_sel:DWORD dst_unused:UNUSED_PAD src0_sel:DWORD src1_sel:WORD_1
	v_or_b32_sdwa v56, v59, v58 dst_sel:DWORD dst_unused:UNUSED_PAD src0_sel:DWORD src1_sel:WORD_1
	v_and_b32_sdwa v59, v72, v55 dst_sel:DWORD dst_unused:UNUSED_PAD src0_sel:WORD_1 src1_sel:DWORD
	v_add3_u32 v61, v72, v59, s27
	v_and_b32_sdwa v59, v75, v55 dst_sel:DWORD dst_unused:UNUSED_PAD src0_sel:WORD_1 src1_sel:DWORD
	v_and_b32_sdwa v62, v73, v55 dst_sel:DWORD dst_unused:UNUSED_PAD src0_sel:WORD_1 src1_sel:DWORD
	v_and_b32_sdwa v58, v74, v55 dst_sel:DWORD dst_unused:UNUSED_PAD src0_sel:WORD_1 src1_sel:DWORD
	v_add3_u32 v59, v75, v59, s27
	v_add3_u32 v62, v73, v62, s27
	v_add3_u32 v58, v74, v58, s27
	v_and_b32_e32 v59, 0xffff0000, v59
	v_and_b32_e32 v62, 0xffff0000, v62
	v_or_b32_sdwa v59, v59, v58 dst_sel:DWORD dst_unused:UNUSED_PAD src0_sel:DWORD src1_sel:WORD_1
	v_or_b32_sdwa v58, v62, v61 dst_sel:DWORD dst_unused:UNUSED_PAD src0_sel:DWORD src1_sel:WORD_1
	global_store_dwordx4 v[80:81], v[56:59], off offset:2048
	s_waitcnt vmcnt(11)
	s_nop 0
	v_mul_f32_e32 v56, v39, v39
	v_mul_f32_e32 v57, v41, v41
	v_fmac_f32_e32 v56, v38, v38
	v_fmac_f32_e32 v57, v40, v40
	v_add_f32_e32 v56, v56, v57
	v_mul_f32_e32 v57, v35, v35
	v_fmac_f32_e32 v57, v34, v34
	v_add_f32_e32 v56, v56, v57
	v_mul_f32_e32 v57, v37, v37
	v_fmac_f32_e32 v57, v36, v36
	v_add_f32_e32 v56, v57, v56
	v_add_f32_e32 v56, v60, v56
	ds_bpermute_b32 v58, v46, v56
	v_and_b32_sdwa v57, v40, v55 dst_sel:DWORD dst_unused:UNUSED_PAD src0_sel:WORD_1 src1_sel:DWORD
	v_add3_u32 v40, v40, v57, s27
	v_and_b32_sdwa v57, v41, v55 dst_sel:DWORD dst_unused:UNUSED_PAD src0_sel:WORD_1 src1_sel:DWORD
	v_add3_u32 v41, v41, v57, s27
	s_waitcnt lgkmcnt(0)
	v_add_f32_e32 v56, v56, v58
	ds_bpermute_b32 v58, v47, v56
	v_and_b32_sdwa v59, v38, v55 dst_sel:DWORD dst_unused:UNUSED_PAD src0_sel:WORD_1 src1_sel:DWORD
	v_add3_u32 v38, v38, v59, s27
	v_and_b32_sdwa v59, v39, v55 dst_sel:DWORD dst_unused:UNUSED_PAD src0_sel:WORD_1 src1_sel:DWORD
	v_add3_u32 v39, v39, v59, s27
	s_waitcnt lgkmcnt(0)
	v_add_f32_e32 v56, v56, v58
	ds_bpermute_b32 v57, v48, v56
	v_and_b32_e32 v41, 0xffff0000, v41
	v_and_b32_e32 v58, 0xffff0000, v39
	v_or_b32_sdwa v39, v41, v40 dst_sel:DWORD dst_unused:UNUSED_PAD src0_sel:DWORD src1_sel:WORD_1
	v_and_b32_sdwa v40, v36, v55 dst_sel:DWORD dst_unused:UNUSED_PAD src0_sel:WORD_1 src1_sel:DWORD
	s_waitcnt lgkmcnt(0)
	v_add_f32_e32 v41, v56, v57
	ds_bpermute_b32 v56, v49, v41
	v_add3_u32 v36, v36, v40, s27
	v_and_b32_sdwa v57, v34, v55 dst_sel:DWORD dst_unused:UNUSED_PAD src0_sel:WORD_1 src1_sel:DWORD
	v_add3_u32 v57, v34, v57, s27
	v_and_b32_sdwa v34, v37, v55 dst_sel:DWORD dst_unused:UNUSED_PAD src0_sel:WORD_1 src1_sel:DWORD
	s_waitcnt lgkmcnt(0)
	v_add_f32_e32 v40, v41, v56
	ds_bpermute_b32 v41, v50, v40
	v_and_b32_sdwa v56, v35, v55 dst_sel:DWORD dst_unused:UNUSED_PAD src0_sel:WORD_1 src1_sel:DWORD
	v_add3_u32 v34, v37, v34, s27
	v_add3_u32 v37, v35, v56, s27
	v_and_b32_e32 v56, 0xffff0000, v34
	s_waitcnt lgkmcnt(0)
	v_add_f32_e32 v34, v40, v41
	ds_bpermute_b32 v35, v51, v34
	v_and_b32_e32 v37, 0xffff0000, v37
	v_or_b32_sdwa v38, v58, v38 dst_sel:DWORD dst_unused:UNUSED_PAD src0_sel:DWORD src1_sel:WORD_1
	v_or_b32_sdwa v41, v56, v36 dst_sel:DWORD dst_unused:UNUSED_PAD src0_sel:DWORD src1_sel:WORD_1
	v_or_b32_sdwa v40, v37, v57 dst_sel:DWORD dst_unused:UNUSED_PAD src0_sel:DWORD src1_sel:WORD_1
	global_store_dwordx4 v[80:81], v[38:41], off offset:3072
	s_and_saveexec_b64 s[20:21], s[6:7]
	s_cbranch_execz .LBB0_52
	s_waitcnt lgkmcnt(0)
	v_add_f32_e32 v34, v34, v35
	s_lshl_b64 s[16:17], s[16:17], 7
	v_cndmask_b32_e64 v36, 0, v34, s[4:5]
	v_lshl_add_u64 v[34:35], v[42:43], 0, s[16:17]
	global_store_dword v[34:35], v36, off
	s_or_b64 exec, exec, s[20:21]
	s_andn2_b64 vcc, exec, s[18:19]
	s_cbranch_vccnz .LBB0_49
	s_branch .LBB0_53

; __device__ __forceinline__ unsigned f2bf(float f) { unsigned u = __float_as_uint(f); return (u + 0x7fffu + ((u >> 16) & 1u)) >> 16; }
; __device__ __forceinline__ void prologue(const Args& a, unsigned char* ws, LAS unsigned char* lds, int gw, int ngw, int wave, int lane) {
;     ...
;         for (int i = gt; i < DEPTH * 8 * DM; i += ngt) { const int l = i / (8 * DM), r = i - l * 8 * DM, h = r / DM, k = r - h * DM;
;             const float v = a.in[6][((size_t)l * DM + k) * INCOLS + FZ_COL + h] * a.in[5][(size_t)l * DM + k];
;             if (NAIVE_MASK & 1) ((float*)(ws + WS_WFZ))[i] = v; else ((bf16_t*)(ws + WS_WFZ))[i] = (bf16_t)f2bf(v); }
.LBB0_61:
	v_ashrrev_i32_e32 v13, 31, v6
	v_ashrrev_i32_e32 v15, 31, v7
	v_lshrrev_b32_e32 v3, 18, v13
	v_lshrrev_b32_e32 v11, 18, v15
	v_add_u32_e32 v3, v6, v3
	v_add_u32_e32 v11, v7, v11
	v_ashrrev_i32_e32 v16, 14, v3
	v_and_b32_e32 v3, 0xffffc000, v3
	v_ashrrev_i32_e32 v18, 14, v11
	v_and_b32_e32 v11, 0xffffc000, v11
	v_sub_u32_e32 v3, v6, v3
	v_sub_u32_e32 v11, v7, v11
	v_ashrrev_i32_e32 v12, 31, v3
	v_ashrrev_i32_e32 v14, 31, v11
	v_lshrrev_b32_e32 v12, 21, v12
	v_lshrrev_b32_e32 v14, 21, v14
	v_add_u32_e32 v12, v3, v12
	v_add_u32_e32 v14, v11, v14
	v_ashrrev_i32_e32 v20, 11, v12
	v_and_b32_e32 v12, 0xfffff800, v12
	v_ashrrev_i32_e32 v17, 31, v16
	v_ashrrev_i32_e32 v22, 11, v14
	v_and_b32_e32 v14, 0xfffff800, v14
	v_sub_u32_e32 v26, v3, v12
	v_ashrrev_i32_e32 v19, 31, v18
	v_lshlrev_b64 v[16:17], 11, v[16:17]
	v_sub_u32_e32 v24, v11, v14
	v_ashrrev_i32_e32 v27, 31, v26
	v_lshlrev_b64 v[18:19], 11, v[18:19]
	v_ashrrev_i32_e32 v25, 31, v24
	v_lshl_add_u64 v[16:17], v[16:17], 0, v[26:27]
	v_lshl_add_u64 v[18:19], v[18:19], 0, v[24:25]
	v_mad_u64_u32 v[24:25], s[20:21], v16, s17, v[4:5]
	v_ashrrev_i32_e32 v21, 31, v20
	v_mad_u64_u32 v[26:27], s[20:21], v18, s17, v[4:5]
	v_mad_i32_i24 v25, v17, s17, v25
	v_lshl_add_u64 v[30:31], v[18:19], 2, s[12:13]
	v_mad_i32_i24 v27, v19, s17, v27
	v_lshl_add_u64 v[18:19], v[20:21], 2, v[24:25]
	v_ashrrev_i32_e32 v23, 31, v22
	v_add_co_u32_e32 v18, vcc, s18, v18
	v_lshl_add_u64 v[20:21], v[22:23], 2, v[26:27]
	s_nop 0
	v_addc_co_u32_e32 v19, vcc, 0, v19, vcc
	v_lshl_add_u64 v[28:29], v[16:17], 2, s[12:13]
	v_add_co_u32_e32 v20, vcc, s18, v20
	global_load_dword v16, v[28:29], off nt
	global_load_dword v17, v[30:31], off nt
	v_addc_co_u32_e32 v21, vcc, 0, v21, vcc
	global_load_dword v22, v[18:19], off nt
	global_load_dword v23, v[20:21], off nt
	v_add_u32_e32 v10, -2, v10
	v_mov_b32_e32 v12, v6
	v_cmp_eq_u32_e32 vcc, 0, v10
	v_mov_b32_e32 v14, v7
	v_lshl_add_u64 v[12:13], v[12:13], 1, s[2:3]
	s_or_b64 s[10:11], vcc, s[10:11]
	v_add_u32_e32 v7, s16, v7
	v_add_u32_e32 v6, s7, v6
	v_lshl_add_u64 v[14:15], v[14:15], 1, s[2:3]
	s_waitcnt vmcnt(0)
	v_pk_mul_f32 v[16:17], v[22:23], v[16:17]
	s_nop 0
	v_and_b32_sdwa v11, v16, v9 dst_sel:DWORD dst_unused:UNUSED_PAD src0_sel:WORD_1 src1_sel:DWORD
	v_and_b32_sdwa v3, v17, v9 dst_sel:DWORD dst_unused:UNUSED_PAD src0_sel:WORD_1 src1_sel:DWORD
	v_add3_u32 v11, v16, v11, s19
	v_add3_u32 v3, v17, v3, s19
	global_store_short_d16_hi v[12:13], v11, off
	global_store_short_d16_hi v[14:15], v3, off
	s_andn2_b64 exec, exec, s[10:11]
	s_cbranch_execnz .LBB0_61
	s_or_b64 exec, exec, s[10:11]
	v_cmp_ne_u32_e32 vcc, v1, v8
	v_mad_u64_u32 v[2:3], s[2:3], v8, s6, v[2:3]
	s_orn2_b64 s[10:11], vcc, exec

; __device__ __forceinline__ unsigned f2bf(float f) { unsigned u = __float_as_uint(f); return (u + 0x7fffu + ((u >> 16) & 1u)) >> 16; }
; __device__ __forceinline__ void prologue(const Args& a, unsigned char* ws, LAS unsigned char* lds, int gw, int ngw, int wave, int lane) {
;     ...
;         for (int i = gt; i < DEPTH * 8 * DM; i += ngt) { const int l = i / (8 * DM), r = i - l * 8 * DM, h = r / DM, k = r - h * DM;
;             const float v = a.in[6][((size_t)l * DM + k) * INCOLS + FZ_COL + h] * a.in[5][(size_t)l * DM + k];
;             if (NAIVE_MASK & 1) ((float*)(ws + WS_WFZ))[i] = v; else ((bf16_t*)(ws + WS_WFZ))[i] = (bf16_t)f2bf(v); }
.LBB0_65:
	v_ashrrev_i32_e32 v1, 31, v2
	v_lshrrev_b32_e32 v1, 18, v1
	v_add_u32_e32 v1, v2, v1
	v_ashrrev_i32_e32 v8, 14, v1
	v_and_b32_e32 v1, 0xffffc000, v1
	v_sub_u32_e32 v3, v2, v1
	v_ashrrev_i32_e32 v10, 31, v3
	v_lshrrev_b32_e32 v10, 21, v10
	v_add_u32_e32 v3, v3, v10
	v_ashrrev_i32_e32 v10, 11, v3
	v_and_b32_e32 v3, 0xfffff800, v3
	v_add_u32_e32 v1, v3, v1
	v_ashrrev_i32_e32 v9, 31, v8
	v_sub_u32_e32 v12, v2, v1
	v_lshlrev_b64 v[8:9], 11, v[8:9]
	v_ashrrev_i32_e32 v13, 31, v12
	v_lshl_add_u64 v[8:9], v[8:9], 0, v[12:13]
	v_mad_u64_u32 v[12:13], s[14:15], v8, s4, v[6:7]
	v_ashrrev_i32_e32 v11, 31, v10
	v_mad_i32_i24 v13, v9, s4, v13
	v_lshl_add_u64 v[14:15], v[8:9], 2, s[12:13]
	v_lshl_add_u64 v[8:9], v[10:11], 2, v[12:13]
	v_add_co_u32_e32 v8, vcc, s5, v8
	global_load_dword v1, v[14:15], off nt
	s_nop 0
	v_addc_co_u32_e32 v9, vcc, 0, v9, vcc
	global_load_dword v3, v[8:9], off nt
	v_add_u32_e32 v2, s6, v2
	v_cmp_lt_i32_e32 vcc, s10, v2
	s_or_b64 s[2:3], vcc, s[2:3]
	s_waitcnt vmcnt(0)
	v_mul_f32_e32 v1, v3, v1
	v_bfe_u32 v3, v1, 16, 1
	v_add3_u32 v1, v1, v3, s7
	global_store_short_d16_hi v[4:5], v1, off
	v_lshl_add_u64 v[4:5], v[4:5], 0, s[0:1]
	s_andn2_b64 exec, exec, s[2:3]
	s_cbranch_execnz .LBB0_65
